# combined: peeled zero-SrcC first K-iteration (no per-tile accumulator zeroing) + chained epilogue store addresses
# speedup vs baseline: 1.0032x; 1.0032x over previous
; DI unsigned pk2(float lo, float hi) { f32x2 v = {lo, hi}; bf16v2 b = __builtin_convertvector(v, bf16v2); return __builtin_bit_cast(unsigned, b); }
; DI float silu_f(float x) { return x * __builtin_amdgcn_rcpf(1.f + __expf(-x)); }
;     DI void operator()(const f32x4 (&acc)[2][2][4][2], const Unit& u, int wr, int wc, int fr, int fq) const {
;         const int row0 = u.pm * BM + wr * 64 + fr, col0 = u.pn * HALF + wc * 32 + 8 * fq;
; #pragma unroll
;         for (int ai = 0; ai < 2; ++ai)
; #pragma unroll
;             for (int m = 0; m < 4; ++m) { bf16_t* rowp = O + (size_t)(row0 + ai * HALF + m * 16) * ldc + col0;
;                 float r[8];
; #pragma unroll
;                 for (int n = 0; n < 2; ++n)
; #pragma unroll
;                     for (int e = 0; e < 4; ++e) { const float g = acc[ai][0][m][n][e], up = acc[ai][1][m][n][e]; r[n * 4 + e] = silu_f(g) * up; }
;                 u32x4 o; o.x = pk2(r[0], r[1]); o.y = pk2(r[2], r[3]); o.z = pk2(r[4], r[5]); o.w = pk2(r[6], r[7]);
;                 *(u32x4*)rowp = o; }
.Lgemm_epi:
	v_lshl_add_u32 v140, s80, 8, v145
	v_ashrrev_i32_e32 v138, 31, v140
	v_mul_lo_u32 v157, s78, v138
	v_mul_lo_u32 v141, s79, v140
	v_mad_u64_u32 v[138:139], s[18:19], s78, v140, 0
	v_or_b32_e32 v162, 16, v140
	v_or_b32_e32 v160, 32, v140
	v_or_b32_e32 v158, 48, v140
	v_add_u32_e32 v154, 0x80, v140
	v_add_u32_e32 v151, 0x90, v140
	v_add3_u32 v139, v139, v157, v141
	s_mov_b64 s[18:19], -1
	s_andn2_b64 vcc, exec, s[14:15]
	v_mul_lo_u32 v163, s79, v162
	v_mul_lo_u32 v161, s79, v160
	v_mul_lo_u32 v159, s79, v158
	v_ashrrev_i32_e32 v156, 31, v154
	v_mul_lo_u32 v155, s79, v154
	v_ashrrev_i32_e32 v153, 31, v151
	v_mul_lo_u32 v152, s79, v151
	v_add_u32_e32 v150, 0xa0, v140
	v_add_u32_e32 v149, 0xb0, v140
	s_cbranch_vccnz .LBB0_746
	s_lshl_b32 s100, s78, 5
	s_mov_b32 s101, 0
	v_mul_f32_e32 v140, 0xbfb8aa3b, v24
	v_mul_f32_e32 v141, 0xbfb8aa3b, v25
	v_mul_f32_e32 v166, 0xbfb8aa3b, v26
	v_mul_f32_e32 v167, 0xbfb8aa3b, v27
	v_mul_f32_e32 v168, 0xbfb8aa3b, v28
	v_mul_f32_e32 v169, 0xbfb8aa3b, v29
	v_exp_f32_e32 v140, v140
	v_exp_f32_e32 v141, v141
	v_exp_f32_e32 v166, v166
	v_exp_f32_e32 v167, v167
	v_exp_f32_e32 v168, v168
	v_exp_f32_e32 v169, v169
	v_mul_f32_e32 v170, 0xbfb8aa3b, v30
	v_mul_f32_e32 v171, 0xbfb8aa3b, v31
	v_add_f32_e32 v140, 1.0, v140
	v_add_f32_e32 v141, 1.0, v141
	v_add_f32_e32 v166, 1.0, v166
	v_add_f32_e32 v167, 1.0, v167
	v_add_f32_e32 v168, 1.0, v168
	v_add_f32_e32 v169, 1.0, v169
	v_exp_f32_e32 v170, v170
	v_exp_f32_e32 v171, v171
	v_rcp_f32_e32 v164, v140
	v_rcp_f32_e32 v165, v141
	v_rcp_f32_e32 v166, v166
	v_rcp_f32_e32 v167, v167
	v_rcp_f32_e32 v168, v168
	v_rcp_f32_e32 v169, v169
	v_add_f32_e32 v170, 1.0, v170
	v_add_f32_e32 v171, 1.0, v171
	v_pk_mul_f32 v[164:165], v[24:25], v[164:165]
	v_pk_mul_f32 v[166:167], v[26:27], v[166:167]
	v_rcp_f32_e32 v170, v170
	v_rcp_f32_e32 v171, v171
	v_pk_mul_f32 v[168:169], v[28:29], v[168:169]
	v_pk_mul_f32 v[164:165], v[164:165], v[88:89]
	v_pk_mul_f32 v[166:167], v[166:167], v[90:91]
	v_pk_mul_f32 v[168:169], v[168:169], v[96:97]
	v_cvt_pk_bf16_f32 v164, v164, v165
	v_cvt_pk_bf16_f32 v165, v166, v167
	v_cvt_pk_bf16_f32 v166, v168, v169
	v_mul_f32_e32 v168, 0xbfb8aa3b, v16
	v_mul_f32_e32 v169, 0xbfb8aa3b, v17
	v_lshl_or_b32 v140, s77, 7, v147
	v_readlane_b32 s18, v255, 30
	v_exp_f32_e32 v168, v168
	v_exp_f32_e32 v169, v169
	v_ashrrev_i32_e32 v141, 31, v140
	v_readlane_b32 s19, v255, 31
	v_pk_mul_f32 v[170:171], v[30:31], v[170:171]
	s_nop 0
	v_lshl_add_u64 v[140:141], v[140:141], 1, s[18:19]
	v_pk_mul_f32 v[170:171], v[170:171], v[98:99]
	v_lshl_add_u64 v[174:175], v[138:139], 1, v[140:141]
	v_cvt_pk_bf16_f32 v167, v170, v171
	global_store_dwordx4 v[174:175], v[164:167], off
	s_nop 1
	v_mul_f32_e32 v170, 0xbfb8aa3b, v20
	v_mul_f32_e32 v171, 0xbfb8aa3b, v21
	v_add_f32_e32 v164, 1.0, v168
	v_add_f32_e32 v165, 1.0, v169
	v_mul_f32_e32 v168, 0xbfb8aa3b, v18
	v_mul_f32_e32 v169, 0xbfb8aa3b, v19
	v_exp_f32_e32 v168, v168
	v_exp_f32_e32 v169, v169
	v_mul_f32_e32 v172, 0xbfb8aa3b, v22
	v_mul_f32_e32 v173, 0xbfb8aa3b, v23
	v_add_f32_e32 v168, 1.0, v168
	v_add_f32_e32 v169, 1.0, v169
	v_exp_f32_e32 v170, v170
	v_exp_f32_e32 v171, v171
	v_exp_f32_e32 v172, v172
	v_exp_f32_e32 v173, v173
	v_rcp_f32_e32 v164, v164
	v_rcp_f32_e32 v165, v165
	v_rcp_f32_e32 v168, v168
	v_rcp_f32_e32 v169, v169
	v_add_f32_e32 v170, 1.0, v170
	v_add_f32_e32 v171, 1.0, v171
	v_add_f32_e32 v172, 1.0, v172
	v_add_f32_e32 v173, 1.0, v173
	v_pk_mul_f32 v[164:165], v[16:17], v[164:165]
	v_pk_mul_f32 v[168:169], v[18:19], v[168:169]
	v_rcp_f32_e32 v170, v170
	v_rcp_f32_e32 v171, v171
	v_rcp_f32_e32 v172, v172
	v_rcp_f32_e32 v173, v173
	v_pk_mul_f32 v[164:165], v[164:165], v[80:81]
	v_pk_mul_f32 v[168:169], v[168:169], v[82:83]
	v_cvt_pk_bf16_f32 v164, v164, v165
	v_cvt_pk_bf16_f32 v165, v168, v169
	v_mul_f32_e32 v168, 0xbfb8aa3b, v8
	v_mul_f32_e32 v169, 0xbfb8aa3b, v9
	v_exp_f32_e32 v168, v168
	v_exp_f32_e32 v169, v169
	v_pk_mul_f32 v[170:171], v[20:21], v[170:171]
	v_pk_mul_f32 v[172:173], v[22:23], v[172:173]
	v_pk_mul_f32 v[170:171], v[170:171], v[84:85]
	v_pk_mul_f32 v[172:173], v[172:173], v[86:87]
	v_lshl_add_u64 v[174:175], v[174:175], 0, s[100:101]
	v_cvt_pk_bf16_f32 v166, v170, v171
	v_cvt_pk_bf16_f32 v167, v172, v173
	global_store_dwordx4 v[174:175], v[164:167], off
	s_nop 1
	v_mul_f32_e32 v170, 0xbfb8aa3b, v12
	v_mul_f32_e32 v171, 0xbfb8aa3b, v13
	v_add_f32_e32 v164, 1.0, v168
	v_add_f32_e32 v165, 1.0, v169
	v_mul_f32_e32 v168, 0xbfb8aa3b, v10
	v_mul_f32_e32 v169, 0xbfb8aa3b, v11
	v_exp_f32_e32 v168, v168
	v_exp_f32_e32 v169, v169
	v_mul_f32_e32 v172, 0xbfb8aa3b, v14
	v_mul_f32_e32 v173, 0xbfb8aa3b, v15
	v_add_f32_e32 v168, 1.0, v168
	v_add_f32_e32 v169, 1.0, v169
	v_exp_f32_e32 v170, v170
	v_exp_f32_e32 v171, v171
	v_exp_f32_e32 v172, v172
	v_exp_f32_e32 v173, v173
	v_rcp_f32_e32 v164, v164
	v_rcp_f32_e32 v165, v165
	v_rcp_f32_e32 v168, v168
	v_rcp_f32_e32 v169, v169
	v_add_f32_e32 v170, 1.0, v170
	v_add_f32_e32 v171, 1.0, v171
	v_add_f32_e32 v172, 1.0, v172
	v_add_f32_e32 v173, 1.0, v173
	v_pk_mul_f32 v[164:165], v[8:9], v[164:165]
	v_pk_mul_f32 v[168:169], v[10:11], v[168:169]
	v_rcp_f32_e32 v170, v170
	v_rcp_f32_e32 v171, v171
	v_rcp_f32_e32 v172, v172
	v_rcp_f32_e32 v173, v173
	v_pk_mul_f32 v[164:165], v[164:165], v[72:73]
	v_pk_mul_f32 v[168:169], v[168:169], v[74:75]
	v_cvt_pk_bf16_f32 v164, v164, v165
	v_cvt_pk_bf16_f32 v165, v168, v169
	v_mul_f32_e32 v168, 0xbfb8aa3b, v0
	v_mul_f32_e32 v169, 0xbfb8aa3b, v1
	v_exp_f32_e32 v168, v168
	v_exp_f32_e32 v169, v169
	v_pk_mul_f32 v[170:171], v[12:13], v[170:171]
	v_pk_mul_f32 v[172:173], v[14:15], v[172:173]
	v_pk_mul_f32 v[170:171], v[170:171], v[76:77]
; DI unsigned pk2(float lo, float hi) { f32x2 v = {lo, hi}; bf16v2 b = __builtin_convertvector(v, bf16v2); return __builtin_bit_cast(unsigned, b); }
; DI float silu_f(float x) { return x * __builtin_amdgcn_rcpf(1.f + __expf(-x)); }
;     DI void operator()(const f32x4 (&acc)[2][2][4][2], const Unit& u, int wr, int wc, int fr, int fq) const {
;     ...
;             for (int m = 0; m < 4; ++m) { bf16_t* rowp = O + (size_t)(row0 + ai * HALF + m * 16) * ldc + col0;
;                 float r[8];
; #pragma unroll
;                 for (int n = 0; n < 2; ++n)
; #pragma unroll
;                     for (int e = 0; e < 4; ++e) { const float g = acc[ai][0][m][n][e], up = acc[ai][1][m][n][e]; r[n * 4 + e] = silu_f(g) * up; }
;                 u32x4 o; o.x = pk2(r[0], r[1]); o.y = pk2(r[2], r[3]); o.z = pk2(r[4], r[5]); o.w = pk2(r[6], r[7]);
;                 *(u32x4*)rowp = o; }
	v_pk_mul_f32 v[172:173], v[172:173], v[78:79]
	v_lshl_add_u64 v[174:175], v[174:175], 0, s[100:101]
	v_cvt_pk_bf16_f32 v166, v170, v171
	v_cvt_pk_bf16_f32 v167, v172, v173
	global_store_dwordx4 v[174:175], v[164:167], off
	s_nop 1
	v_mul_f32_e32 v170, 0xbfb8aa3b, v4
	v_mul_f32_e32 v171, 0xbfb8aa3b, v5
	v_add_f32_e32 v164, 1.0, v168
	v_add_f32_e32 v165, 1.0, v169
	v_mul_f32_e32 v168, 0xbfb8aa3b, v2
	v_mul_f32_e32 v169, 0xbfb8aa3b, v3
	v_mul_f32_e32 v172, 0xbfb8aa3b, v6
	v_mul_f32_e32 v173, 0xbfb8aa3b, v7
	v_exp_f32_e32 v168, v168
	v_exp_f32_e32 v169, v169
	v_exp_f32_e32 v170, v170
	v_exp_f32_e32 v171, v171
	v_exp_f32_e32 v172, v172
	v_exp_f32_e32 v173, v173
	v_add_f32_e32 v168, 1.0, v168
	v_add_f32_e32 v169, 1.0, v169
	v_add_f32_e32 v170, 1.0, v170
	v_add_f32_e32 v171, 1.0, v171
	v_add_f32_e32 v172, 1.0, v172
	v_add_f32_e32 v173, 1.0, v173
	v_rcp_f32_e32 v164, v164
	v_rcp_f32_e32 v165, v165
	v_rcp_f32_e32 v168, v168
	v_rcp_f32_e32 v169, v169
	v_rcp_f32_e32 v170, v170
	v_rcp_f32_e32 v171, v171
	v_rcp_f32_e32 v172, v172
	v_rcp_f32_e32 v173, v173
	v_pk_mul_f32 v[164:165], v[0:1], v[164:165]
	v_pk_mul_f32 v[168:169], v[2:3], v[168:169]
	v_pk_mul_f32 v[170:171], v[4:5], v[170:171]
	v_pk_mul_f32 v[172:173], v[6:7], v[172:173]
	v_pk_mul_f32 v[164:165], v[164:165], v[56:57]
	v_pk_mul_f32 v[168:169], v[168:169], v[58:59]
	v_pk_mul_f32 v[170:171], v[170:171], v[64:65]
	v_pk_mul_f32 v[172:173], v[172:173], v[66:67]
	v_lshl_add_u64 v[174:175], v[174:175], 0, s[100:101]
	v_cvt_pk_bf16_f32 v164, v164, v165
	v_cvt_pk_bf16_f32 v165, v168, v169
	v_cvt_pk_bf16_f32 v166, v170, v171
	v_cvt_pk_bf16_f32 v167, v172, v173
	global_store_dwordx4 v[174:175], v[164:167], off
	s_nop 1
	v_mul_f32_e32 v169, 0xbfb8aa3b, v63
	v_mul_f32_e32 v164, 0xbfb8aa3b, v60
	v_mul_f32_e32 v165, 0xbfb8aa3b, v61
	v_mul_f32_e32 v168, 0xbfb8aa3b, v62
	v_mul_f32_e32 v170, 0xbfb8aa3b, v68
	v_mul_f32_e32 v171, 0xbfb8aa3b, v69
	v_mul_f32_e32 v172, 0xbfb8aa3b, v70
	v_mul_f32_e32 v173, 0xbfb8aa3b, v71
	v_exp_f32_e32 v164, v164
	v_exp_f32_e32 v165, v165
	v_exp_f32_e32 v168, v168
	v_exp_f32_e32 v169, v169
	v_exp_f32_e32 v170, v170
	v_exp_f32_e32 v171, v171
	v_exp_f32_e32 v172, v172
	v_exp_f32_e32 v173, v173
	v_add_f32_e32 v164, 1.0, v164
	v_add_f32_e32 v165, 1.0, v165
	v_add_f32_e32 v168, 1.0, v168
	v_add_f32_e32 v169, 1.0, v169
	v_add_f32_e32 v170, 1.0, v170
	v_add_f32_e32 v171, 1.0, v171
	v_add_f32_e32 v172, 1.0, v172
	v_add_f32_e32 v173, 1.0, v173
	v_rcp_f32_e32 v164, v164
	v_rcp_f32_e32 v165, v165
	v_rcp_f32_e32 v168, v168
	v_rcp_f32_e32 v169, v169
	v_rcp_f32_e32 v170, v170
	v_rcp_f32_e32 v171, v171
	v_rcp_f32_e32 v172, v172
	v_rcp_f32_e32 v173, v173
	v_pk_mul_f32 v[164:165], v[60:61], v[164:165]
	v_pk_mul_f32 v[168:169], v[62:63], v[168:169]
	v_pk_mul_f32 v[170:171], v[68:69], v[170:171]
	v_pk_mul_f32 v[172:173], v[70:71], v[172:173]
	v_pk_mul_f32 v[164:165], v[164:165], v[120:121]
	v_pk_mul_f32 v[168:169], v[168:169], v[122:123]
	v_pk_mul_f32 v[170:171], v[170:171], v[124:125]
	v_pk_mul_f32 v[172:173], v[172:173], v[126:127]
	s_mul_i32 vcc_lo, s78, 0xa0
	s_mov_b32 vcc_hi, 0
	v_lshl_add_u64 v[174:175], v[174:175], 0, vcc
	v_cvt_pk_bf16_f32 v164, v164, v165
	v_cvt_pk_bf16_f32 v165, v168, v169
	v_cvt_pk_bf16_f32 v166, v170, v171
	v_cvt_pk_bf16_f32 v167, v172, v173
	global_store_dwordx4 v[174:175], v[164:167], off
	s_nop 1
	v_mul_f32_e32 v169, 0xbfb8aa3b, v51
	v_mul_f32_e32 v164, 0xbfb8aa3b, v48
	v_mul_f32_e32 v165, 0xbfb8aa3b, v49
	v_mul_f32_e32 v168, 0xbfb8aa3b, v50
	v_mul_f32_e32 v170, 0xbfb8aa3b, v52
	v_mul_f32_e32 v171, 0xbfb8aa3b, v53
	v_mul_f32_e32 v172, 0xbfb8aa3b, v54
	v_mul_f32_e32 v173, 0xbfb8aa3b, v55
	v_exp_f32_e32 v164, v164
	v_exp_f32_e32 v165, v165
	v_exp_f32_e32 v168, v168
	v_exp_f32_e32 v169, v169
	v_exp_f32_e32 v170, v170
	v_exp_f32_e32 v171, v171
	v_exp_f32_e32 v172, v172
	v_exp_f32_e32 v173, v173
	v_add_f32_e32 v164, 1.0, v164
	v_add_f32_e32 v165, 1.0, v165
	v_add_f32_e32 v168, 1.0, v168
	v_add_f32_e32 v169, 1.0, v169
	v_add_f32_e32 v170, 1.0, v170
	v_add_f32_e32 v171, 1.0, v171
	v_add_f32_e32 v172, 1.0, v172
	v_add_f32_e32 v173, 1.0, v173
; DI unsigned pk2(float lo, float hi) { f32x2 v = {lo, hi}; bf16v2 b = __builtin_convertvector(v, bf16v2); return __builtin_bit_cast(unsigned, b); }
; DI float silu_f(float x) { return x * __builtin_amdgcn_rcpf(1.f + __expf(-x)); }
;     DI void operator()(const f32x4 (&acc)[2][2][4][2], const Unit& u, int wr, int wc, int fr, int fq) const {
;     ...
;             for (int m = 0; m < 4; ++m) { bf16_t* rowp = O + (size_t)(row0 + ai * HALF + m * 16) * ldc + col0;
;                 float r[8];
; #pragma unroll
;                 for (int n = 0; n < 2; ++n)
; #pragma unroll
;                     for (int e = 0; e < 4; ++e) { const float g = acc[ai][0][m][n][e], up = acc[ai][1][m][n][e]; r[n * 4 + e] = silu_f(g) * up; }
;                 u32x4 o; o.x = pk2(r[0], r[1]); o.y = pk2(r[2], r[3]); o.z = pk2(r[4], r[5]); o.w = pk2(r[6], r[7]);
;                 *(u32x4*)rowp = o; }
	v_rcp_f32_e32 v164, v164
	v_rcp_f32_e32 v165, v165
	v_rcp_f32_e32 v168, v168
	v_rcp_f32_e32 v169, v169
	v_rcp_f32_e32 v170, v170
	v_rcp_f32_e32 v171, v171
	v_rcp_f32_e32 v172, v172
	v_rcp_f32_e32 v173, v173
	v_pk_mul_f32 v[164:165], v[48:49], v[164:165]
	v_pk_mul_f32 v[168:169], v[50:51], v[168:169]
	v_pk_mul_f32 v[170:171], v[52:53], v[170:171]
	v_pk_mul_f32 v[172:173], v[54:55], v[172:173]
	v_pk_mul_f32 v[164:165], v[164:165], v[112:113]
	v_pk_mul_f32 v[168:169], v[168:169], v[114:115]
	v_pk_mul_f32 v[170:171], v[170:171], v[116:117]
	v_pk_mul_f32 v[172:173], v[172:173], v[118:119]
	v_lshl_add_u64 v[174:175], v[174:175], 0, s[100:101]
	v_cvt_pk_bf16_f32 v164, v164, v165
	v_cvt_pk_bf16_f32 v165, v168, v169
	v_cvt_pk_bf16_f32 v166, v170, v171
	v_cvt_pk_bf16_f32 v167, v172, v173
	global_store_dwordx4 v[174:175], v[164:167], off
	s_nop 1
	v_mul_f32_e32 v170, 0xbfb8aa3b, v44
	v_mul_f32_e32 v164, 0xbfb8aa3b, v40
	v_mul_f32_e32 v165, 0xbfb8aa3b, v41
	v_mul_f32_e32 v168, 0xbfb8aa3b, v42
	v_mul_f32_e32 v169, 0xbfb8aa3b, v43
	v_mul_f32_e32 v171, 0xbfb8aa3b, v45
	v_mul_f32_e32 v172, 0xbfb8aa3b, v46
	v_mul_f32_e32 v173, 0xbfb8aa3b, v47
	v_exp_f32_e32 v164, v164
	v_exp_f32_e32 v165, v165
	v_exp_f32_e32 v168, v168
	v_exp_f32_e32 v169, v169
	v_exp_f32_e32 v170, v170
	v_exp_f32_e32 v171, v171
	v_exp_f32_e32 v172, v172
	v_exp_f32_e32 v173, v173
	v_add_f32_e32 v164, 1.0, v164
	v_add_f32_e32 v165, 1.0, v165
	v_add_f32_e32 v168, 1.0, v168
	v_add_f32_e32 v169, 1.0, v169
	v_add_f32_e32 v170, 1.0, v170
	v_add_f32_e32 v171, 1.0, v171
	v_add_f32_e32 v172, 1.0, v172
	v_add_f32_e32 v173, 1.0, v173
	v_rcp_f32_e32 v164, v164
	v_rcp_f32_e32 v165, v165
	v_rcp_f32_e32 v168, v168
	v_rcp_f32_e32 v169, v169
	v_rcp_f32_e32 v170, v170
	v_rcp_f32_e32 v171, v171
	v_rcp_f32_e32 v172, v172
	v_rcp_f32_e32 v173, v173
	v_pk_mul_f32 v[164:165], v[40:41], v[164:165]
	v_pk_mul_f32 v[168:169], v[42:43], v[168:169]
	v_pk_mul_f32 v[170:171], v[44:45], v[170:171]
	v_pk_mul_f32 v[172:173], v[46:47], v[172:173]
	v_pk_mul_f32 v[164:165], v[164:165], v[104:105]
	v_pk_mul_f32 v[168:169], v[168:169], v[106:107]
	v_pk_mul_f32 v[170:171], v[170:171], v[108:109]
	v_pk_mul_f32 v[172:173], v[172:173], v[110:111]
	v_lshl_add_u64 v[174:175], v[174:175], 0, s[100:101]
	v_cvt_pk_bf16_f32 v164, v164, v165
	v_cvt_pk_bf16_f32 v165, v168, v169
	v_cvt_pk_bf16_f32 v166, v170, v171
	v_cvt_pk_bf16_f32 v167, v172, v173
	global_store_dwordx4 v[174:175], v[164:167], off
	s_nop 1
	v_mul_f32_e32 v170, 0xbfb8aa3b, v36
	v_mul_f32_e32 v164, 0xbfb8aa3b, v32
	v_mul_f32_e32 v165, 0xbfb8aa3b, v33
	v_mul_f32_e32 v168, 0xbfb8aa3b, v34
	v_mul_f32_e32 v169, 0xbfb8aa3b, v35
	v_mul_f32_e32 v171, 0xbfb8aa3b, v37
	v_mul_f32_e32 v172, 0xbfb8aa3b, v38
	v_mul_f32_e32 v173, 0xbfb8aa3b, v39
	v_exp_f32_e32 v164, v164
	v_exp_f32_e32 v165, v165
	v_exp_f32_e32 v168, v168
	v_exp_f32_e32 v169, v169
	v_exp_f32_e32 v170, v170
	v_exp_f32_e32 v171, v171
	v_exp_f32_e32 v172, v172
	v_exp_f32_e32 v173, v173
	v_add_f32_e32 v164, 1.0, v164
	v_add_f32_e32 v165, 1.0, v165
	v_add_f32_e32 v168, 1.0, v168
	v_add_f32_e32 v169, 1.0, v169
	v_add_f32_e32 v170, 1.0, v170
	v_add_f32_e32 v171, 1.0, v171
	v_add_f32_e32 v172, 1.0, v172
	v_add_f32_e32 v173, 1.0, v173
	v_rcp_f32_e32 v164, v164
	v_rcp_f32_e32 v165, v165
	v_rcp_f32_e32 v168, v168
	v_rcp_f32_e32 v169, v169
	v_rcp_f32_e32 v170, v170
	v_rcp_f32_e32 v171, v171
	v_rcp_f32_e32 v172, v172
	v_rcp_f32_e32 v173, v173
	v_pk_mul_f32 v[164:165], v[32:33], v[164:165]
	v_pk_mul_f32 v[168:169], v[34:35], v[168:169]
	v_pk_mul_f32 v[170:171], v[36:37], v[170:171]
	v_pk_mul_f32 v[172:173], v[38:39], v[172:173]
	v_pk_mul_f32 v[164:165], v[164:165], v[92:93]
	v_pk_mul_f32 v[168:169], v[168:169], v[94:95]
	v_pk_mul_f32 v[170:171], v[170:171], v[100:101]
	v_pk_mul_f32 v[172:173], v[172:173], v[102:103]
	v_lshl_add_u64 v[174:175], v[174:175], 0, s[100:101]
	v_cvt_pk_bf16_f32 v164, v164, v165
	v_cvt_pk_bf16_f32 v165, v168, v169
	v_cvt_pk_bf16_f32 v166, v170, v171
	v_cvt_pk_bf16_f32 v167, v172, v173
	global_store_dwordx4 v[174:175], v[164:167], off
	s_nop 1
	s_cbranch_execnz .LBB0_748
	s_branch .LBB0_747
